# v19 + epilogue row-scale (ss) loads prefetched in the last K iteration of swiglu/scale GEMM units
# speedup vs baseline: 1.0066x; 1.0037x over previous
.LBB0_725:
	s_add_u32 s26, s24, 0xfff80080
	s_addc_u32 s27, s25, -1
	s_add_i32 s49, 0, 0x10000
	s_cmp_eq_u32 s48, 28
	s_cselect_b32 s29, s7, s27
	s_cselect_b32 s28, s19, s26
	v_add_u32_e32 v0, s49, v145
	s_cselect_b32 s27, s17, s47
	s_cselect_b32 s26, s45, s46
	s_add_i32 s52, 0, 0x14000
	ds_read_b128 v[140:143], v0
	ds_read_b128 v[148:151], v0 offset:1024
	ds_read_b128 v[152:155], v0 offset:2048
	ds_read_b128 v[156:159], v0 offset:3072
	v_add_u32_e32 v0, s52, v145
	ds_read_b128 v[160:163], v0
	ds_read_b128 v[164:167], v0 offset:1024
	ds_read_b128 v[178:181], v0 offset:2048
	ds_read_b128 v[182:185], v0 offset:3072
	v_lshl_add_u64 v[168:169], s[24:25], 0, v[136:137]
	s_add_i32 m0, s9, 0xc000
	ds_read_b128 v[186:189], v146
	ds_read_b128 v[190:193], v146 offset:1024
	ds_read_b128 v[194:197], v146 offset:2048
	ds_read_b128 v[198:201], v146 offset:3072
	ds_read_b128 v[202:205], v146 offset:4096
	ds_read_b128 v[206:209], v146 offset:5120
	ds_read_b128 v[226:229], v146 offset:6144
	ds_read_b128 v[230:233], v146 offset:7168
	global_load_lds_dwordx4 v[168:169], off
	v_lshl_add_u64 v[168:169], s[24:25], 0, v[138:139]
	s_add_i32 m0, s9, 0xe000
	s_nop 0
	global_load_lds_dwordx4 v[168:169], off
	s_waitcnt vmcnt(8)
	s_waitcnt lgkmcnt(0)
	s_barrier
	s_setprio 1
	s_waitcnt lgkmcnt(0)
	v_mfma_f32_16x16x32_bf16 v[126:129], v[140:143], v[186:189], v[126:129]
	v_mfma_f32_16x16x32_bf16 v[122:125], v[152:155], v[186:189], v[122:125]
	v_mfma_f32_16x16x32_bf16 v[110:113], v[140:143], v[194:197], v[110:113]
	v_mfma_f32_16x16x32_bf16 v[106:109], v[152:155], v[194:197], v[106:109]
	v_mfma_f32_16x16x32_bf16 v[94:97], v[140:143], v[202:205], v[94:97]
	v_mfma_f32_16x16x32_bf16 v[90:93], v[152:155], v[202:205], v[90:93]
	v_mfma_f32_16x16x32_bf16 v[78:81], v[140:143], v[226:229], v[78:81]
	v_mfma_f32_16x16x32_bf16 v[74:77], v[152:155], v[226:229], v[74:77]
	v_mfma_f32_16x16x32_bf16 v[126:129], v[148:151], v[190:193], v[126:129]
	v_mfma_f32_16x16x32_bf16 v[122:125], v[156:159], v[190:193], v[122:125]
	v_mfma_f32_16x16x32_bf16 v[110:113], v[148:151], v[198:201], v[110:113]
	v_mfma_f32_16x16x32_bf16 v[106:109], v[156:159], v[198:201], v[106:109]
	v_mfma_f32_16x16x32_bf16 v[94:97], v[148:151], v[206:209], v[94:97]
	v_mfma_f32_16x16x32_bf16 v[90:93], v[156:159], v[206:209], v[90:93]
	v_mfma_f32_16x16x32_bf16 v[78:81], v[148:151], v[230:233], v[78:81]
	v_mfma_f32_16x16x32_bf16 v[74:77], v[156:159], v[230:233], v[74:77]
	s_setprio 0
	s_setprio 1
	v_mfma_f32_16x16x32_bf16 v[118:121], v[160:163], v[186:189], v[118:121]
	v_mfma_f32_16x16x32_bf16 v[114:117], v[178:181], v[186:189], v[114:117]
	v_mfma_f32_16x16x32_bf16 v[102:105], v[160:163], v[194:197], v[102:105]
	v_mfma_f32_16x16x32_bf16 v[98:101], v[178:181], v[194:197], v[98:101]
	v_mfma_f32_16x16x32_bf16 v[86:89], v[160:163], v[202:205], v[86:89]
	v_mfma_f32_16x16x32_bf16 v[82:85], v[178:181], v[202:205], v[82:85]
	v_mfma_f32_16x16x32_bf16 v[70:73], v[160:163], v[226:229], v[70:73]
	v_mfma_f32_16x16x32_bf16 v[66:69], v[178:181], v[226:229], v[66:69]
	v_mfma_f32_16x16x32_bf16 v[118:121], v[164:167], v[190:193], v[118:121]
	v_mfma_f32_16x16x32_bf16 v[114:117], v[182:185], v[190:193], v[114:117]
	v_mfma_f32_16x16x32_bf16 v[102:105], v[164:167], v[198:201], v[102:105]
	v_mfma_f32_16x16x32_bf16 v[98:101], v[182:185], v[198:201], v[98:101]
	v_mfma_f32_16x16x32_bf16 v[86:89], v[164:167], v[206:209], v[86:89]
	v_mfma_f32_16x16x32_bf16 v[82:85], v[182:185], v[206:209], v[82:85]
	v_mfma_f32_16x16x32_bf16 v[70:73], v[164:167], v[230:233], v[70:73]
	v_mfma_f32_16x16x32_bf16 v[66:69], v[182:185], v[230:233], v[66:69]
	s_setprio 0
	s_barrier
	s_add_i32 s49, s49, s3
	v_lshl_add_u64 v[168:169], s[26:27], 0, v[130:131]
	s_mov_b32 m0, s49
	ds_read_b128 v[186:189], v146 offset:16384
	ds_read_b128 v[190:193], v146 offset:17408
	ds_read_b128 v[194:197], v146 offset:18432
	ds_read_b128 v[198:201], v146 offset:19456
	ds_read_b128 v[202:205], v146 offset:20480
	ds_read_b128 v[206:209], v146 offset:21504
	ds_read_b128 v[226:229], v146 offset:22528
	ds_read_b128 v[230:233], v146 offset:23552
	global_load_lds_dwordx4 v[168:169], off
	s_add_i32 m0, s49, 0x2000
	s_add_u32 s64, s26, 0x80000
	v_lshl_add_u64 v[210:211], s[26:27], 0, v[132:133]
	s_addc_u32 s65, s27, 0
	s_add_i32 s49, s52, s3
	global_load_lds_dwordx4 v[210:211], off
	v_lshl_add_u64 v[234:235], s[64:65], 0, v[130:131]
	s_mov_b32 m0, s49
	v_lshl_add_u64 v[236:237], s[28:29], 0, v[132:133]
	global_load_lds_dwordx4 v[234:235], off
	v_lshl_add_u64 v[234:235], s[64:65], 0, v[132:133]
	s_add_i32 m0, s49, 0x2000
	s_nop 0
	global_load_lds_dwordx4 v[234:235], off
	v_lshl_add_u64 v[234:235], s[28:29], 0, v[130:131]
	s_mov_b32 m0, s9
	s_nop 0
	global_load_lds_dwordx4 v[234:235], off
	s_mov_b32 m0, s30
	s_nop 0
	global_load_lds_dwordx4 v[236:237], off
	s_waitcnt vmcnt(8)
	s_waitcnt lgkmcnt(0)
	s_barrier
	s_setprio 1
	s_waitcnt lgkmcnt(0)
	v_mfma_f32_16x16x32_bf16 v[62:65], v[140:143], v[186:189], v[62:65]
	v_mfma_f32_16x16x32_bf16 v[58:61], v[152:155], v[186:189], v[58:61]
	v_mfma_f32_16x16x32_bf16 v[46:49], v[140:143], v[194:197], v[46:49]
	v_mfma_f32_16x16x32_bf16 v[42:45], v[152:155], v[194:197], v[42:45]
	v_mfma_f32_16x16x32_bf16 v[30:33], v[140:143], v[202:205], v[30:33]
	v_mfma_f32_16x16x32_bf16 v[26:29], v[152:155], v[202:205], v[26:29]
	v_mfma_f32_16x16x32_bf16 v[14:17], v[140:143], v[226:229], v[14:17]
	v_mfma_f32_16x16x32_bf16 v[10:13], v[152:155], v[226:229], v[10:13]
	v_mfma_f32_16x16x32_bf16 v[62:65], v[148:151], v[190:193], v[62:65]
	v_mfma_f32_16x16x32_bf16 v[58:61], v[156:159], v[190:193], v[58:61]
	v_mfma_f32_16x16x32_bf16 v[46:49], v[148:151], v[198:201], v[46:49]
	v_mfma_f32_16x16x32_bf16 v[42:45], v[156:159], v[198:201], v[42:45]
	v_mfma_f32_16x16x32_bf16 v[30:33], v[148:151], v[206:209], v[30:33]
	v_mfma_f32_16x16x32_bf16 v[26:29], v[156:159], v[206:209], v[26:29]
	v_mfma_f32_16x16x32_bf16 v[14:17], v[148:151], v[230:233], v[14:17]
	v_mfma_f32_16x16x32_bf16 v[10:13], v[156:159], v[230:233], v[10:13]
	s_setprio 0
	s_setprio 1
	v_mfma_f32_16x16x32_bf16 v[54:57], v[160:163], v[186:189], v[54:57]
	v_mfma_f32_16x16x32_bf16 v[50:53], v[178:181], v[186:189], v[50:53]
	v_mfma_f32_16x16x32_bf16 v[38:41], v[160:163], v[194:197], v[38:41]
	v_mfma_f32_16x16x32_bf16 v[34:37], v[178:181], v[194:197], v[34:37]
	v_mfma_f32_16x16x32_bf16 v[22:25], v[160:163], v[202:205], v[22:25]
	v_mfma_f32_16x16x32_bf16 v[18:21], v[178:181], v[202:205], v[18:21]
	v_mfma_f32_16x16x32_bf16 v[6:9], v[160:163], v[226:229], v[6:9]
	v_mfma_f32_16x16x32_bf16 v[2:5], v[178:181], v[226:229], v[2:5]
	v_mfma_f32_16x16x32_bf16 v[54:57], v[164:167], v[190:193], v[54:57]
	v_mfma_f32_16x16x32_bf16 v[50:53], v[182:185], v[190:193], v[50:53]
	v_mfma_f32_16x16x32_bf16 v[38:41], v[164:167], v[198:201], v[38:41]
	v_mfma_f32_16x16x32_bf16 v[34:37], v[182:185], v[198:201], v[34:37]
	v_mfma_f32_16x16x32_bf16 v[22:25], v[164:167], v[206:209], v[22:25]
	v_mfma_f32_16x16x32_bf16 v[18:21], v[182:185], v[206:209], v[18:21]
	v_mfma_f32_16x16x32_bf16 v[6:9], v[164:167], v[230:233], v[6:9]
	v_mfma_f32_16x16x32_bf16 v[2:5], v[182:185], v[230:233], v[2:5]
	s_setprio 0
	s_barrier
	s_add_i32 s49, 0, 0x18000
	v_add_u32_e32 v0, s49, v145
	s_add_i32 s52, 0, 0x1c000
	ds_read_b128 v[140:143], v0
	ds_read_b128 v[148:151], v0 offset:1024
	ds_read_b128 v[152:155], v0 offset:2048
	ds_read_b128 v[156:159], v0 offset:3072
	v_add_u32_e32 v0, s52, v145
	ds_read_b128 v[160:163], v0
	ds_read_b128 v[164:167], v0 offset:1024
	ds_read_b128 v[178:181], v0 offset:2048
	ds_read_b128 v[182:185], v0 offset:3072
	s_add_u32 s28, s28, 0x80000
	s_addc_u32 s29, s29, 0
	s_mov_b32 m0, s31
	v_lshl_add_u64 v[238:239], s[28:29], 0, v[130:131]
	ds_read_b128 v[186:189], v146 offset:32768
	ds_read_b128 v[190:193], v146 offset:33792
	ds_read_b128 v[194:197], v146 offset:34816
	ds_read_b128 v[198:201], v146 offset:35840
	ds_read_b128 v[202:205], v146 offset:36864
	ds_read_b128 v[206:209], v146 offset:37888
	ds_read_b128 v[226:229], v146 offset:38912
	ds_read_b128 v[230:233], v146 offset:39936
	global_load_lds_dwordx4 v[238:239], off
	v_lshl_add_u64 v[238:239], s[28:29], 0, v[132:133]
	s_mov_b32 m0, s34
	s_nop 0
	global_load_lds_dwordx4 v[238:239], off
	s_waitcnt vmcnt(8)
	s_waitcnt lgkmcnt(0)
	s_barrier
	s_setprio 1
	s_waitcnt lgkmcnt(0)
	v_mfma_f32_16x16x32_bf16 v[126:129], v[140:143], v[186:189], v[126:129]
	v_mfma_f32_16x16x32_bf16 v[122:125], v[152:155], v[186:189], v[122:125]
	v_mfma_f32_16x16x32_bf16 v[110:113], v[140:143], v[194:197], v[110:113]
	v_mfma_f32_16x16x32_bf16 v[106:109], v[152:155], v[194:197], v[106:109]
	v_mfma_f32_16x16x32_bf16 v[94:97], v[140:143], v[202:205], v[94:97]
	v_mfma_f32_16x16x32_bf16 v[90:93], v[152:155], v[202:205], v[90:93]
	v_mfma_f32_16x16x32_bf16 v[78:81], v[140:143], v[226:229], v[78:81]
	v_mfma_f32_16x16x32_bf16 v[74:77], v[152:155], v[226:229], v[74:77]
	v_mfma_f32_16x16x32_bf16 v[126:129], v[148:151], v[190:193], v[126:129]
	v_mfma_f32_16x16x32_bf16 v[122:125], v[156:159], v[190:193], v[122:125]
	v_mfma_f32_16x16x32_bf16 v[110:113], v[148:151], v[198:201], v[110:113]
	v_mfma_f32_16x16x32_bf16 v[106:109], v[156:159], v[198:201], v[106:109]
	v_mfma_f32_16x16x32_bf16 v[94:97], v[148:151], v[206:209], v[94:97]
	v_mfma_f32_16x16x32_bf16 v[90:93], v[156:159], v[206:209], v[90:93]
	v_mfma_f32_16x16x32_bf16 v[78:81], v[148:151], v[230:233], v[78:81]
	v_mfma_f32_16x16x32_bf16 v[74:77], v[156:159], v[230:233], v[74:77]
	s_setprio 0
	s_setprio 1
	v_mfma_f32_16x16x32_bf16 v[118:121], v[160:163], v[186:189], v[118:121]
	v_mfma_f32_16x16x32_bf16 v[114:117], v[178:181], v[186:189], v[114:117]
	v_mfma_f32_16x16x32_bf16 v[102:105], v[160:163], v[194:197], v[102:105]
	v_mfma_f32_16x16x32_bf16 v[98:101], v[178:181], v[194:197], v[98:101]
	v_mfma_f32_16x16x32_bf16 v[86:89], v[160:163], v[202:205], v[86:89]
	v_mfma_f32_16x16x32_bf16 v[82:85], v[178:181], v[202:205], v[82:85]
	v_mfma_f32_16x16x32_bf16 v[70:73], v[160:163], v[226:229], v[70:73]
	v_mfma_f32_16x16x32_bf16 v[66:69], v[178:181], v[226:229], v[66:69]
	v_mfma_f32_16x16x32_bf16 v[118:121], v[164:167], v[190:193], v[118:121]
	v_mfma_f32_16x16x32_bf16 v[114:117], v[182:185], v[190:193], v[114:117]
	v_mfma_f32_16x16x32_bf16 v[102:105], v[164:167], v[198:201], v[102:105]
	v_mfma_f32_16x16x32_bf16 v[98:101], v[182:185], v[198:201], v[98:101]
	v_mfma_f32_16x16x32_bf16 v[86:89], v[164:167], v[206:209], v[86:89]
	v_mfma_f32_16x16x32_bf16 v[82:85], v[182:185], v[206:209], v[82:85]
	v_mfma_f32_16x16x32_bf16 v[70:73], v[164:167], v[230:233], v[70:73]
	v_mfma_f32_16x16x32_bf16 v[66:69], v[182:185], v[230:233], v[66:69]
	s_setprio 0
	s_barrier
	s_add_i32 s28, s49, s3
	v_lshl_add_u64 v[168:169], v[168:169], 0, s[50:51]
	s_mov_b32 m0, s28
	ds_read_b128 v[186:189], v146 offset:49152
	ds_read_b128 v[190:193], v146 offset:50176
	ds_read_b128 v[194:197], v146 offset:51200
	ds_read_b128 v[198:201], v146 offset:52224
	ds_read_b128 v[202:205], v146 offset:53248
	ds_read_b128 v[206:209], v146 offset:54272
	ds_read_b128 v[226:229], v146 offset:55296
	ds_read_b128 v[230:233], v146 offset:56320
	global_load_lds_dwordx4 v[168:169], off
	s_add_i32 m0, s28, 0x2000
	s_add_u32 s26, s26, 0x80080
	v_lshl_add_u64 v[168:169], v[210:211], 0, s[50:51]
	s_addc_u32 s27, s27, 0
	s_add_i32 s28, s52, s3
	global_load_lds_dwordx4 v[168:169], off
	v_lshl_add_u64 v[168:169], s[26:27], 0, v[130:131]
	s_mov_b32 m0, s28
	s_nop 0
	global_load_lds_dwordx4 v[168:169], off
	v_lshl_add_u64 v[168:169], s[26:27], 0, v[132:133]
	s_add_i32 m0, s28, 0x2000
	s_nop 0
	global_load_lds_dwordx4 v[168:169], off
	v_lshl_add_u64 v[168:169], v[234:235], 0, s[50:51]
	s_mov_b32 m0, s35
	s_nop 0
	global_load_lds_dwordx4 v[168:169], off
	v_lshl_add_u64 v[168:169], v[236:237], 0, s[50:51]
	s_mov_b32 m0, s36
	s_nop 0
	global_load_lds_dwordx4 v[168:169], off
	s_waitcnt vmcnt(8)
	s_waitcnt lgkmcnt(0)
	s_cmp_lg_u32 s48, 28
	s_cbranch_scc1 .Lmy_rs_g1
	v_lshl_add_u32 v248, s6, 8, v135
	v_ashrrev_i32_e32 v249, 31, v248
	v_lshl_add_u64 v[248:249], v[248:249], 2, s[12:13]
	global_load_dword v240, v[248:249], off
	global_load_dword v241, v[248:249], off offset:64
	global_load_dword v242, v[248:249], off offset:128
	global_load_dword v243, v[248:249], off offset:192
	global_load_dword v244, v[248:249], off offset:512
	global_load_dword v245, v[248:249], off offset:576
	global_load_dword v246, v[248:249], off offset:640
	global_load_dword v247, v[248:249], off offset:704
.Lmy_rs_g1:
	s_barrier
	s_setprio 1
	s_waitcnt lgkmcnt(0)
	v_mfma_f32_16x16x32_bf16 v[62:65], v[140:143], v[186:189], v[62:65]
	v_mfma_f32_16x16x32_bf16 v[58:61], v[152:155], v[186:189], v[58:61]
	v_mfma_f32_16x16x32_bf16 v[46:49], v[140:143], v[194:197], v[46:49]
	v_mfma_f32_16x16x32_bf16 v[42:45], v[152:155], v[194:197], v[42:45]
	v_mfma_f32_16x16x32_bf16 v[30:33], v[140:143], v[202:205], v[30:33]
	v_mfma_f32_16x16x32_bf16 v[26:29], v[152:155], v[202:205], v[26:29]
	v_mfma_f32_16x16x32_bf16 v[14:17], v[140:143], v[226:229], v[14:17]
	v_mfma_f32_16x16x32_bf16 v[10:13], v[152:155], v[226:229], v[10:13]
	v_mfma_f32_16x16x32_bf16 v[62:65], v[148:151], v[190:193], v[62:65]
	v_mfma_f32_16x16x32_bf16 v[58:61], v[156:159], v[190:193], v[58:61]
	v_mfma_f32_16x16x32_bf16 v[46:49], v[148:151], v[198:201], v[46:49]
	v_mfma_f32_16x16x32_bf16 v[42:45], v[156:159], v[198:201], v[42:45]
	v_mfma_f32_16x16x32_bf16 v[30:33], v[148:151], v[206:209], v[30:33]
	v_mfma_f32_16x16x32_bf16 v[26:29], v[156:159], v[206:209], v[26:29]
	v_mfma_f32_16x16x32_bf16 v[14:17], v[148:151], v[230:233], v[14:17]
	v_mfma_f32_16x16x32_bf16 v[10:13], v[156:159], v[230:233], v[10:13]
	s_setprio 0
	s_setprio 1
	v_mfma_f32_16x16x32_bf16 v[54:57], v[160:163], v[186:189], v[54:57]
	v_mfma_f32_16x16x32_bf16 v[50:53], v[178:181], v[186:189], v[50:53]
	v_mfma_f32_16x16x32_bf16 v[38:41], v[160:163], v[194:197], v[38:41]
	v_mfma_f32_16x16x32_bf16 v[34:37], v[178:181], v[194:197], v[34:37]
	v_mfma_f32_16x16x32_bf16 v[22:25], v[160:163], v[202:205], v[22:25]
	v_mfma_f32_16x16x32_bf16 v[18:21], v[178:181], v[202:205], v[18:21]
	v_mfma_f32_16x16x32_bf16 v[6:9], v[160:163], v[226:229], v[6:9]
	v_mfma_f32_16x16x32_bf16 v[2:5], v[178:181], v[226:229], v[2:5]
	v_mfma_f32_16x16x32_bf16 v[54:57], v[164:167], v[190:193], v[54:57]
	v_mfma_f32_16x16x32_bf16 v[50:53], v[182:185], v[190:193], v[50:53]
	v_mfma_f32_16x16x32_bf16 v[38:41], v[164:167], v[198:201], v[38:41]
	v_mfma_f32_16x16x32_bf16 v[34:37], v[182:185], v[198:201], v[34:37]
	v_mfma_f32_16x16x32_bf16 v[22:25], v[164:167], v[206:209], v[22:25]
	v_mfma_f32_16x16x32_bf16 v[18:21], v[182:185], v[206:209], v[18:21]
	v_mfma_f32_16x16x32_bf16 v[6:9], v[164:167], v[230:233], v[6:9]
	v_mfma_f32_16x16x32_bf16 v[2:5], v[182:185], v[230:233], v[2:5]
	s_setprio 0
	s_barrier
	s_add_i32 s48, s48, 2
	s_add_u32 s24, s24, 0x100
	s_addc_u32 s25, s25, 0
	s_add_u32 s46, s46, 0x100
	s_addc_u32 s47, s47, 0
	s_cmp_gt_u32 s48, 29
	s_cbranch_scc0 .LBB0_725
	s_and_b64 vcc, exec, s[14:15]
	s_cbranch_vccz .LBB0_728
	s_barrier
.LBB0_728:
	v_lshl_add_u32 v142, s6, 8, v135
	v_ashrrev_i32_e32 v143, 31, v142
	v_readlane_b32 s19, v251, 5
	s_cmp_ge_i32 s8, s19
	s_cselect_b64 s[26:27], -1, 0
	v_readlane_b32 s28, v251, 6
	v_readlane_b32 s48, v251, 0
	v_readlane_b32 s46, v251, 3
	s_mov_b64 s[6:7], -1
	s_and_b64 vcc, exec, s[26:27]
	v_lshlrev_b32_e32 v140, 2, v134
	v_readlane_b32 s29, v251, 7
	v_readlane_b32 s49, v251, 1
	v_readlane_b32 s47, v251, 4
	s_waitcnt vmcnt(0)
	v_mov_b32_e32 v0, v240
	v_mov_b32_e32 v153, v241
	v_mov_b32_e32 v152, v242
	v_mov_b32_e32 v151, v243
	v_mov_b32_e32 v150, v244
	v_mov_b32_e32 v149, v245
	v_mov_b32_e32 v148, v246
	v_mov_b32_e32 v147, v247
	v_fmamk_f32 v0, v0, 0x3a000000, v214
	v_rsq_f32_e32 v144, v0
	s_cbranch_vccz .LBB0_730
	v_mul_lo_u32 v0, s47, v142
	v_mul_lo_u32 v141, s46, v143
	v_mad_u64_u32 v[154:155], s[6:7], s46, v142, 0
	v_add3_u32 v155, v155, v141, v0
	s_sub_i32 s6, s8, s19
	v_lshl_add_u64 v[154:155], v[154:155], 2, s[48:49]
	s_lshl_b32 s52, s6, 8
	v_lshl_add_u64 v[154:155], s[52:53], 2, v[154:155]
	v_mov_b32_e32 v141, v1
	v_lshl_add_u64 v[158:159], v[154:155], 0, v[140:141]
	v_pk_mul_f32 v[156:157], v[128:129], v[144:145] op_sel_hi:[1,0]
	v_pk_mul_f32 v[154:155], v[126:127], v[144:145] op_sel_hi:[1,0]
	global_store_dwordx4 v[158:159], v[154:157], off
	s_mov_b64 s[6:7], 0
	s_nop 0
	v_pk_mul_f32 v[156:157], v[124:125], v[144:145] op_sel_hi:[1,0]
	v_pk_mul_f32 v[154:155], v[122:123], v[144:145] op_sel_hi:[1,0]
	global_store_dwordx4 v[158:159], v[154:157], off offset:64
	s_nop 1
	v_pk_mul_f32 v[156:157], v[120:121], v[144:145] op_sel_hi:[1,0]
	v_pk_mul_f32 v[154:155], v[118:119], v[144:145] op_sel_hi:[1,0]
	global_store_dwordx4 v[158:159], v[154:157], off offset:512
	s_nop 1
	v_pk_mul_f32 v[156:157], v[116:117], v[144:145] op_sel_hi:[1,0]
	v_pk_mul_f32 v[154:155], v[114:115], v[144:145] op_sel_hi:[1,0]
	global_store_dwordx4 v[158:159], v[154:157], off offset:576

.LBB0_1475:
	s_add_u32 s22, s20, 0xfff80080
	s_addc_u32 s23, s21, -1
	s_add_i32 s42, 0, 0x10000
	s_cmp_eq_u32 s41, 28
	s_cselect_b32 s25, s13, s23
	s_cselect_b32 s24, s37, s22
	s_cselect_b32 s23, s11, s40
	s_cselect_b32 s22, s38, s39
	s_add_i32 s44, 0, 0x14000
	v_add_u32_e32 v156, s42, v145
	v_add_u32_e32 v168, s44, v145
	ds_read_b128 v[140:143], v156
	ds_read_b128 v[148:151], v156 offset:1024
	ds_read_b128 v[152:155], v156 offset:2048
	ds_read_b128 v[156:159], v156 offset:3072
	ds_read_b128 v[160:163], v168
	ds_read_b128 v[164:167], v168 offset:1024
	ds_read_b128 v[178:181], v168 offset:2048
	ds_read_b128 v[182:185], v168 offset:3072
	v_lshl_add_u64 v[168:169], s[20:21], 0, v[136:137]
	s_add_i32 m0, s27, 0xc000
	ds_read_b128 v[186:189], v147
	ds_read_b128 v[190:193], v147 offset:1024
	ds_read_b128 v[194:197], v147 offset:2048
	ds_read_b128 v[198:201], v147 offset:3072
	ds_read_b128 v[202:205], v147 offset:4096
	ds_read_b128 v[206:209], v147 offset:5120
	ds_read_b128 v[226:229], v147 offset:6144
	ds_read_b128 v[230:233], v147 offset:7168
	global_load_lds_dwordx4 v[168:169], off
	v_lshl_add_u64 v[168:169], s[20:21], 0, v[138:139]
	s_add_i32 m0, s27, 0xe000
	s_nop 0
	global_load_lds_dwordx4 v[168:169], off
	s_waitcnt vmcnt(8)
	s_waitcnt lgkmcnt(0)
	s_barrier
	s_setprio 1
	s_waitcnt lgkmcnt(0)
	v_mfma_f32_16x16x32_bf16 v[126:129], v[140:143], v[186:189], v[126:129]
	v_mfma_f32_16x16x32_bf16 v[122:125], v[152:155], v[186:189], v[122:125]
	v_mfma_f32_16x16x32_bf16 v[110:113], v[140:143], v[194:197], v[110:113]
	v_mfma_f32_16x16x32_bf16 v[102:105], v[152:155], v[194:197], v[102:105]
	v_mfma_f32_16x16x32_bf16 v[94:97], v[140:143], v[202:205], v[94:97]
	v_mfma_f32_16x16x32_bf16 v[86:89], v[152:155], v[202:205], v[86:89]
	v_mfma_f32_16x16x32_bf16 v[78:81], v[140:143], v[226:229], v[78:81]
	v_mfma_f32_16x16x32_bf16 v[70:73], v[152:155], v[226:229], v[70:73]
	v_mfma_f32_16x16x32_bf16 v[126:129], v[148:151], v[190:193], v[126:129]
	v_mfma_f32_16x16x32_bf16 v[122:125], v[156:159], v[190:193], v[122:125]
	v_mfma_f32_16x16x32_bf16 v[110:113], v[148:151], v[198:201], v[110:113]
	v_mfma_f32_16x16x32_bf16 v[102:105], v[156:159], v[198:201], v[102:105]
	v_mfma_f32_16x16x32_bf16 v[94:97], v[148:151], v[206:209], v[94:97]
	v_mfma_f32_16x16x32_bf16 v[86:89], v[156:159], v[206:209], v[86:89]
	v_mfma_f32_16x16x32_bf16 v[78:81], v[148:151], v[230:233], v[78:81]
	v_mfma_f32_16x16x32_bf16 v[70:73], v[156:159], v[230:233], v[70:73]
	s_setprio 0
	s_setprio 1
	v_mfma_f32_16x16x32_bf16 v[118:121], v[160:163], v[186:189], v[118:121]
	v_mfma_f32_16x16x32_bf16 v[114:117], v[178:181], v[186:189], v[114:117]
	v_mfma_f32_16x16x32_bf16 v[106:109], v[160:163], v[194:197], v[106:109]
	v_mfma_f32_16x16x32_bf16 v[98:101], v[178:181], v[194:197], v[98:101]
	v_mfma_f32_16x16x32_bf16 v[90:93], v[160:163], v[202:205], v[90:93]
	v_mfma_f32_16x16x32_bf16 v[82:85], v[178:181], v[202:205], v[82:85]
	v_mfma_f32_16x16x32_bf16 v[74:77], v[160:163], v[226:229], v[74:77]
	v_mfma_f32_16x16x32_bf16 v[66:69], v[178:181], v[226:229], v[66:69]
	v_mfma_f32_16x16x32_bf16 v[118:121], v[164:167], v[190:193], v[118:121]
	v_mfma_f32_16x16x32_bf16 v[114:117], v[182:185], v[190:193], v[114:117]
	v_mfma_f32_16x16x32_bf16 v[106:109], v[164:167], v[198:201], v[106:109]
	v_mfma_f32_16x16x32_bf16 v[98:101], v[182:185], v[198:201], v[98:101]
	v_mfma_f32_16x16x32_bf16 v[90:93], v[164:167], v[206:209], v[90:93]
	v_mfma_f32_16x16x32_bf16 v[82:85], v[182:185], v[206:209], v[82:85]
	v_mfma_f32_16x16x32_bf16 v[74:77], v[164:167], v[230:233], v[74:77]
	v_mfma_f32_16x16x32_bf16 v[66:69], v[182:185], v[230:233], v[66:69]
	s_setprio 0
	s_barrier
	s_add_i32 s42, s42, s26
	v_lshl_add_u64 v[168:169], s[22:23], 0, v[0:1]
	s_mov_b32 m0, s42
	ds_read_b128 v[186:189], v147 offset:16384
	ds_read_b128 v[190:193], v147 offset:17408
	ds_read_b128 v[194:197], v147 offset:18432
	ds_read_b128 v[198:201], v147 offset:19456
	ds_read_b128 v[202:205], v147 offset:20480
	ds_read_b128 v[206:209], v147 offset:21504
	ds_read_b128 v[226:229], v147 offset:22528
	ds_read_b128 v[230:233], v147 offset:23552
	global_load_lds_dwordx4 v[168:169], off
	s_add_i32 m0, s42, 0x2000
	s_add_u32 s42, s22, 0x80000
	v_lshl_add_u64 v[210:211], s[22:23], 0, v[134:135]
	s_addc_u32 s43, s23, 0
	s_add_i32 s44, s44, s26
	global_load_lds_dwordx4 v[210:211], off
	v_lshl_add_u64 v[234:235], s[42:43], 0, v[0:1]
	s_mov_b32 m0, s44
	v_lshl_add_u64 v[236:237], s[24:25], 0, v[132:133]
	global_load_lds_dwordx4 v[234:235], off
	v_lshl_add_u64 v[234:235], s[42:43], 0, v[134:135]
	s_add_i32 m0, s44, 0x2000
	s_nop 0
	global_load_lds_dwordx4 v[234:235], off
	v_lshl_add_u64 v[234:235], s[24:25], 0, v[130:131]
	s_mov_b32 m0, s27
	s_nop 0
	global_load_lds_dwordx4 v[234:235], off
	s_mov_b32 m0, s28
	s_nop 0
	global_load_lds_dwordx4 v[236:237], off
	s_waitcnt vmcnt(8)
	s_waitcnt lgkmcnt(0)
	s_barrier
	s_setprio 1
	s_waitcnt lgkmcnt(0)
	v_mfma_f32_16x16x32_bf16 v[62:65], v[140:143], v[186:189], v[62:65]
	v_mfma_f32_16x16x32_bf16 v[54:57], v[152:155], v[186:189], v[54:57]
	v_mfma_f32_16x16x32_bf16 v[46:49], v[140:143], v[194:197], v[46:49]
	v_mfma_f32_16x16x32_bf16 v[38:41], v[152:155], v[194:197], v[38:41]
	v_mfma_f32_16x16x32_bf16 v[30:33], v[140:143], v[202:205], v[30:33]
	v_mfma_f32_16x16x32_bf16 v[22:25], v[152:155], v[202:205], v[22:25]
	v_mfma_f32_16x16x32_bf16 v[14:17], v[140:143], v[226:229], v[14:17]
	v_mfma_f32_16x16x32_bf16 v[6:9], v[152:155], v[226:229], v[6:9]
	v_mfma_f32_16x16x32_bf16 v[62:65], v[148:151], v[190:193], v[62:65]
	v_mfma_f32_16x16x32_bf16 v[54:57], v[156:159], v[190:193], v[54:57]
	v_mfma_f32_16x16x32_bf16 v[46:49], v[148:151], v[198:201], v[46:49]
	v_mfma_f32_16x16x32_bf16 v[38:41], v[156:159], v[198:201], v[38:41]
	v_mfma_f32_16x16x32_bf16 v[30:33], v[148:151], v[206:209], v[30:33]
	v_mfma_f32_16x16x32_bf16 v[22:25], v[156:159], v[206:209], v[22:25]
	v_mfma_f32_16x16x32_bf16 v[14:17], v[148:151], v[230:233], v[14:17]
	v_mfma_f32_16x16x32_bf16 v[6:9], v[156:159], v[230:233], v[6:9]
	s_setprio 0
	s_setprio 1
	v_mfma_f32_16x16x32_bf16 v[58:61], v[160:163], v[186:189], v[58:61]
	v_mfma_f32_16x16x32_bf16 v[50:53], v[178:181], v[186:189], v[50:53]
	v_mfma_f32_16x16x32_bf16 v[42:45], v[160:163], v[194:197], v[42:45]
	v_mfma_f32_16x16x32_bf16 v[34:37], v[178:181], v[194:197], v[34:37]
	v_mfma_f32_16x16x32_bf16 v[26:29], v[160:163], v[202:205], v[26:29]
	v_mfma_f32_16x16x32_bf16 v[18:21], v[178:181], v[202:205], v[18:21]
	v_mfma_f32_16x16x32_bf16 v[10:13], v[160:163], v[226:229], v[10:13]
	v_mfma_f32_16x16x32_bf16 v[2:5], v[178:181], v[226:229], v[2:5]
	v_mfma_f32_16x16x32_bf16 v[58:61], v[164:167], v[190:193], v[58:61]
	v_mfma_f32_16x16x32_bf16 v[50:53], v[182:185], v[190:193], v[50:53]
	v_mfma_f32_16x16x32_bf16 v[42:45], v[164:167], v[198:201], v[42:45]
	v_mfma_f32_16x16x32_bf16 v[34:37], v[182:185], v[198:201], v[34:37]
	v_mfma_f32_16x16x32_bf16 v[26:29], v[164:167], v[206:209], v[26:29]
	v_mfma_f32_16x16x32_bf16 v[18:21], v[182:185], v[206:209], v[18:21]
	v_mfma_f32_16x16x32_bf16 v[10:13], v[164:167], v[230:233], v[10:13]
	v_mfma_f32_16x16x32_bf16 v[2:5], v[182:185], v[230:233], v[2:5]
	s_setprio 0
	s_barrier
	s_add_i32 s42, 0, 0x18000
	s_add_i32 s43, 0, 0x1c000
	v_add_u32_e32 v156, s42, v145
	v_add_u32_e32 v177, s43, v145
	ds_read_b128 v[140:143], v156
	ds_read_b128 v[148:151], v156 offset:1024
	ds_read_b128 v[152:155], v156 offset:2048
	ds_read_b128 v[156:159], v156 offset:3072
	ds_read_b128 v[160:163], v177
	ds_read_b128 v[164:167], v177 offset:1024
	ds_read_b128 v[178:181], v177 offset:2048
	ds_read_b128 v[182:185], v177 offset:3072
	s_add_u32 s24, s24, 0x80000
	s_addc_u32 s25, s25, 0
	s_mov_b32 m0, s29
	v_lshl_add_u64 v[238:239], s[24:25], 0, v[130:131]
	ds_read_b128 v[186:189], v147 offset:32768
	ds_read_b128 v[190:193], v147 offset:33792
	ds_read_b128 v[194:197], v147 offset:34816
	ds_read_b128 v[198:201], v147 offset:35840
	ds_read_b128 v[202:205], v147 offset:36864
	ds_read_b128 v[206:209], v147 offset:37888
	ds_read_b128 v[226:229], v147 offset:38912
	ds_read_b128 v[230:233], v147 offset:39936
	global_load_lds_dwordx4 v[238:239], off
	v_lshl_add_u64 v[238:239], s[24:25], 0, v[132:133]
	s_mov_b32 m0, s30
	s_nop 0
	global_load_lds_dwordx4 v[238:239], off
	s_waitcnt vmcnt(8)
	s_waitcnt lgkmcnt(0)
	s_barrier
	s_setprio 1
	s_waitcnt lgkmcnt(0)
	v_mfma_f32_16x16x32_bf16 v[126:129], v[140:143], v[186:189], v[126:129]
	v_mfma_f32_16x16x32_bf16 v[122:125], v[152:155], v[186:189], v[122:125]
	v_mfma_f32_16x16x32_bf16 v[110:113], v[140:143], v[194:197], v[110:113]
	v_mfma_f32_16x16x32_bf16 v[102:105], v[152:155], v[194:197], v[102:105]
	v_mfma_f32_16x16x32_bf16 v[94:97], v[140:143], v[202:205], v[94:97]
	v_mfma_f32_16x16x32_bf16 v[86:89], v[152:155], v[202:205], v[86:89]
	v_mfma_f32_16x16x32_bf16 v[78:81], v[140:143], v[226:229], v[78:81]
	v_mfma_f32_16x16x32_bf16 v[70:73], v[152:155], v[226:229], v[70:73]
	v_mfma_f32_16x16x32_bf16 v[126:129], v[148:151], v[190:193], v[126:129]
	v_mfma_f32_16x16x32_bf16 v[122:125], v[156:159], v[190:193], v[122:125]
	v_mfma_f32_16x16x32_bf16 v[110:113], v[148:151], v[198:201], v[110:113]
	v_mfma_f32_16x16x32_bf16 v[102:105], v[156:159], v[198:201], v[102:105]
	v_mfma_f32_16x16x32_bf16 v[94:97], v[148:151], v[206:209], v[94:97]
	v_mfma_f32_16x16x32_bf16 v[86:89], v[156:159], v[206:209], v[86:89]
	v_mfma_f32_16x16x32_bf16 v[78:81], v[148:151], v[230:233], v[78:81]
	v_mfma_f32_16x16x32_bf16 v[70:73], v[156:159], v[230:233], v[70:73]
	s_setprio 0
	s_setprio 1
	v_mfma_f32_16x16x32_bf16 v[118:121], v[160:163], v[186:189], v[118:121]
	v_mfma_f32_16x16x32_bf16 v[114:117], v[178:181], v[186:189], v[114:117]
	v_mfma_f32_16x16x32_bf16 v[106:109], v[160:163], v[194:197], v[106:109]
	v_mfma_f32_16x16x32_bf16 v[98:101], v[178:181], v[194:197], v[98:101]
	v_mfma_f32_16x16x32_bf16 v[90:93], v[160:163], v[202:205], v[90:93]
	v_mfma_f32_16x16x32_bf16 v[82:85], v[178:181], v[202:205], v[82:85]
	v_mfma_f32_16x16x32_bf16 v[74:77], v[160:163], v[226:229], v[74:77]
	v_mfma_f32_16x16x32_bf16 v[66:69], v[178:181], v[226:229], v[66:69]
	v_mfma_f32_16x16x32_bf16 v[118:121], v[164:167], v[190:193], v[118:121]
	v_mfma_f32_16x16x32_bf16 v[114:117], v[182:185], v[190:193], v[114:117]
	v_mfma_f32_16x16x32_bf16 v[106:109], v[164:167], v[198:201], v[106:109]
	v_mfma_f32_16x16x32_bf16 v[98:101], v[182:185], v[198:201], v[98:101]
	v_mfma_f32_16x16x32_bf16 v[90:93], v[164:167], v[206:209], v[90:93]
	v_mfma_f32_16x16x32_bf16 v[82:85], v[182:185], v[206:209], v[82:85]
	v_mfma_f32_16x16x32_bf16 v[74:77], v[164:167], v[230:233], v[74:77]
	v_mfma_f32_16x16x32_bf16 v[66:69], v[182:185], v[230:233], v[66:69]
	s_setprio 0
	s_barrier
	s_add_i32 s24, s42, s26
	v_lshl_add_u64 v[168:169], v[168:169], 0, s[50:51]
	s_mov_b32 m0, s24
	ds_read_b128 v[186:189], v147 offset:49152
	ds_read_b128 v[190:193], v147 offset:50176
	ds_read_b128 v[194:197], v147 offset:51200
	ds_read_b128 v[198:201], v147 offset:52224
	ds_read_b128 v[202:205], v147 offset:53248
	ds_read_b128 v[206:209], v147 offset:54272
	ds_read_b128 v[226:229], v147 offset:55296
	ds_read_b128 v[230:233], v147 offset:56320
	global_load_lds_dwordx4 v[168:169], off
	s_add_i32 m0, s24, 0x2000
	s_add_u32 s22, s22, 0x80080
	v_lshl_add_u64 v[168:169], v[210:211], 0, s[50:51]
	s_addc_u32 s23, s23, 0
	s_add_i32 s24, s43, s26
	global_load_lds_dwordx4 v[168:169], off
	v_lshl_add_u64 v[168:169], s[22:23], 0, v[0:1]
	s_mov_b32 m0, s24
	s_nop 0
	global_load_lds_dwordx4 v[168:169], off
	v_lshl_add_u64 v[168:169], s[22:23], 0, v[134:135]
	s_add_i32 m0, s24, 0x2000
	s_nop 0
	global_load_lds_dwordx4 v[168:169], off
	v_lshl_add_u64 v[168:169], v[234:235], 0, s[50:51]
	s_mov_b32 m0, s31
	s_nop 0
	global_load_lds_dwordx4 v[168:169], off
	v_lshl_add_u64 v[168:169], v[236:237], 0, s[50:51]
	s_mov_b32 m0, s34
	s_nop 0
	global_load_lds_dwordx4 v[168:169], off
	s_waitcnt vmcnt(8)
	s_waitcnt lgkmcnt(0)
	s_cmp_lg_u32 s41, 28
	s_cbranch_scc1 .Lmy_rs_g3
	v_lshl_add_u32 v248, s18, 8, v144
	v_ashrrev_i32_e32 v249, 31, v248
	v_lshl_add_u64 v[248:249], v[248:249], 2, s[6:7]
	global_load_dword v240, v[248:249], off
	global_load_dword v241, v[248:249], off offset:64
	global_load_dword v242, v[248:249], off offset:128
	global_load_dword v243, v[248:249], off offset:192
	global_load_dword v244, v[248:249], off offset:512
	global_load_dword v245, v[248:249], off offset:576
	global_load_dword v246, v[248:249], off offset:640
	global_load_dword v247, v[248:249], off offset:704
.Lmy_rs_g3:
	s_barrier
	s_setprio 1
	s_waitcnt lgkmcnt(0)
	v_mfma_f32_16x16x32_bf16 v[62:65], v[140:143], v[186:189], v[62:65]
	v_mfma_f32_16x16x32_bf16 v[54:57], v[152:155], v[186:189], v[54:57]
	v_mfma_f32_16x16x32_bf16 v[46:49], v[140:143], v[194:197], v[46:49]
	v_mfma_f32_16x16x32_bf16 v[38:41], v[152:155], v[194:197], v[38:41]
	v_mfma_f32_16x16x32_bf16 v[30:33], v[140:143], v[202:205], v[30:33]
	v_mfma_f32_16x16x32_bf16 v[22:25], v[152:155], v[202:205], v[22:25]
	v_mfma_f32_16x16x32_bf16 v[14:17], v[140:143], v[226:229], v[14:17]
	v_mfma_f32_16x16x32_bf16 v[6:9], v[152:155], v[226:229], v[6:9]
	v_mfma_f32_16x16x32_bf16 v[62:65], v[148:151], v[190:193], v[62:65]
	v_mfma_f32_16x16x32_bf16 v[54:57], v[156:159], v[190:193], v[54:57]
	v_mfma_f32_16x16x32_bf16 v[46:49], v[148:151], v[198:201], v[46:49]
	v_mfma_f32_16x16x32_bf16 v[38:41], v[156:159], v[198:201], v[38:41]
	v_mfma_f32_16x16x32_bf16 v[30:33], v[148:151], v[206:209], v[30:33]
	v_mfma_f32_16x16x32_bf16 v[22:25], v[156:159], v[206:209], v[22:25]
	v_mfma_f32_16x16x32_bf16 v[14:17], v[148:151], v[230:233], v[14:17]
	v_mfma_f32_16x16x32_bf16 v[6:9], v[156:159], v[230:233], v[6:9]
	s_setprio 0
	s_setprio 1
	v_mfma_f32_16x16x32_bf16 v[58:61], v[160:163], v[186:189], v[58:61]
	v_mfma_f32_16x16x32_bf16 v[50:53], v[178:181], v[186:189], v[50:53]
	v_mfma_f32_16x16x32_bf16 v[42:45], v[160:163], v[194:197], v[42:45]
	v_mfma_f32_16x16x32_bf16 v[34:37], v[178:181], v[194:197], v[34:37]
	v_mfma_f32_16x16x32_bf16 v[26:29], v[160:163], v[202:205], v[26:29]
	v_mfma_f32_16x16x32_bf16 v[18:21], v[178:181], v[202:205], v[18:21]
	v_mfma_f32_16x16x32_bf16 v[10:13], v[160:163], v[226:229], v[10:13]
	v_mfma_f32_16x16x32_bf16 v[2:5], v[178:181], v[226:229], v[2:5]
	v_mfma_f32_16x16x32_bf16 v[58:61], v[164:167], v[190:193], v[58:61]
	v_mfma_f32_16x16x32_bf16 v[50:53], v[182:185], v[190:193], v[50:53]
	v_mfma_f32_16x16x32_bf16 v[42:45], v[164:167], v[198:201], v[42:45]
	v_mfma_f32_16x16x32_bf16 v[34:37], v[182:185], v[198:201], v[34:37]
	v_mfma_f32_16x16x32_bf16 v[26:29], v[164:167], v[206:209], v[26:29]
	v_mfma_f32_16x16x32_bf16 v[18:21], v[182:185], v[206:209], v[18:21]
	v_mfma_f32_16x16x32_bf16 v[10:13], v[164:167], v[230:233], v[10:13]
	v_mfma_f32_16x16x32_bf16 v[2:5], v[182:185], v[230:233], v[2:5]
	s_setprio 0
	s_barrier
	s_add_i32 s41, s41, 2
	s_add_u32 s20, s20, 0x100
	s_addc_u32 s21, s21, 0
	s_add_u32 s39, s39, 0x100
	s_addc_u32 s40, s40, 0
	s_cmp_gt_u32 s41, 29
	s_cbranch_scc0 .LBB0_1475
	s_and_b64 vcc, exec, s[8:9]
	s_cbranch_vccz .LBB0_1478
	s_barrier
.LBB0_1478:
	v_lshl_add_u32 v140, s18, 8, v144
	v_lshl_or_b32 v142, s19, 7, v146
	v_ashrrev_i32_e32 v143, 31, v142
	v_or_b32_e32 v159, 16, v140
	v_or_b32_e32 v157, 32, v140
	v_or_b32_e32 v155, 48, v140
	v_add_u32_e32 v153, 0x80, v140
	v_add_u32_e32 v151, 0x90, v140
	v_add_u32_e32 v149, 0xa0, v140
	v_add_u32_e32 v141, 0xb0, v140
	s_andn2_b64 vcc, exec, s[4:5]
	s_waitcnt vmcnt(0)
	v_mov_b32_e32 v160, v240
	v_mov_b32_e32 v161, v241
	v_mov_b32_e32 v158, v242
	v_mov_b32_e32 v156, v243
	v_mov_b32_e32 v154, v244
	v_mov_b32_e32 v152, v245
	v_mov_b32_e32 v150, v246
	v_mov_b32_e32 v148, v247
	v_fmamk_f32 v160, v160, 0x3a000000, v214
	v_rsq_f32_e32 v160, v160
	s_nop 0
	v_pk_mul_f32 v[126:127], v[126:127], v[160:161] op_sel_hi:[1,0]
	s_nop 0
	v_mul_f32_e32 v162, 0xbfb8aa3b, v126
	v_mul_f32_e32 v163, 0xbfb8aa3b, v127
	v_exp_f32_e32 v162, v162
	v_exp_f32_e32 v163, v163
	v_pk_mul_f32 v[118:119], v[118:119], v[160:161] op_sel_hi:[1,0]
	v_pk_mul_f32 v[120:121], v[120:121], v[160:161] op_sel_hi:[1,0]
	v_add_f32_e32 v162, 1.0, v162
	v_add_f32_e32 v163, 1.0, v163
	v_rcp_f32_e32 v162, v162
	v_rcp_f32_e32 v163, v163
	v_pk_mul_f32 v[122:123], v[122:123], v[160:161] op_sel_hi:[1,0]
	v_pk_mul_f32 v[114:115], v[114:115], v[160:161] op_sel_hi:[1,0]
	v_pk_mul_f32 v[116:117], v[116:117], v[160:161] op_sel_hi:[1,0]
	v_pk_mul_f32 v[126:127], v[126:127], v[162:163]
	s_nop 0
	v_pk_mul_f32 v[118:119], v[118:119], v[126:127]
	v_pk_mul_f32 v[126:127], v[128:129], v[160:161] op_sel_hi:[1,0]
	s_nop 0
	v_mul_f32_e32 v128, 0xbfb8aa3b, v126
	v_mul_f32_e32 v129, 0xbfb8aa3b, v127
	v_exp_f32_e32 v128, v128
	v_exp_f32_e32 v129, v129
	v_add_f32_e32 v128, 1.0, v128
	v_add_f32_e32 v129, 1.0, v129
	v_rcp_f32_e32 v128, v128
	v_rcp_f32_e32 v129, v129
	s_nop 0
	v_pk_mul_f32 v[126:127], v[126:127], v[128:129]
	s_nop 0
	v_pk_mul_f32 v[120:121], v[120:121], v[126:127]
	v_mul_f32_e32 v126, 0xbfb8aa3b, v122
	v_mul_f32_e32 v127, 0xbfb8aa3b, v123
	v_exp_f32_e32 v126, v126
	v_exp_f32_e32 v127, v127
	v_add_f32_e32 v126, 1.0, v126
	v_add_f32_e32 v127, 1.0, v127
	v_rcp_f32_e32 v126, v126
	v_rcp_f32_e32 v127, v127
	s_nop 0
	v_pk_mul_f32 v[122:123], v[122:123], v[126:127]
	s_nop 0
	v_pk_mul_f32 v[122:123], v[114:115], v[122:123]
	v_pk_mul_f32 v[114:115], v[124:125], v[160:161] op_sel_hi:[1,0]
	s_nop 0
	v_mul_f32_e32 v124, 0xbfb8aa3b, v114
	v_mul_f32_e32 v125, 0xbfb8aa3b, v115
	v_exp_f32_e32 v124, v124
	v_exp_f32_e32 v125, v125
	v_add_f32_e32 v124, 1.0, v124
	v_add_f32_e32 v125, 1.0, v125
	v_rcp_f32_e32 v124, v124
	v_rcp_f32_e32 v125, v125
	s_nop 0
	v_pk_mul_f32 v[114:115], v[114:115], v[124:125]
	s_nop 0
	v_pk_mul_f32 v[124:125], v[116:117], v[114:115]
	v_cvt_pk_bf16_f32 v114, v118, v119
	v_mov_b64_e32 v[118:119], s[58:59]
	v_cvt_pk_bf16_f32 v115, v120, v121
	v_cvt_pk_bf16_f32 v116, v122, v123
	v_mad_i64_i32 v[122:123], s[18:19], v140, s71, v[118:119]
	v_lshlrev_b64 v[120:121], 1, v[142:143]
	v_cvt_pk_bf16_f32 v117, v124, v125
	v_lshl_add_u64 v[122:123], v[122:123], 0, v[120:121]
	global_store_dwordx4 v[122:123], v[114:117], off
	s_nop 1
	v_fmamk_f32 v114, v161, 0x3a000000, v214
	v_rsq_f32_e32 v114, v114
	s_nop 0
	v_pk_mul_f32 v[110:111], v[110:111], v[114:115] op_sel_hi:[1,0]
	s_nop 0
	v_mul_f32_e32 v115, 0xbfb8aa3b, v110
	v_exp_f32_e32 v115, v115
	s_nop 0
	v_add_f32_e32 v115, 1.0, v115
	v_rcp_f32_e32 v116, v115
	v_pk_mul_f32 v[106:107], v[106:107], v[114:115] op_sel_hi:[1,0]
	v_mul_f32_e32 v115, 0xbfb8aa3b, v111
	v_exp_f32_e32 v115, v115
	s_nop 0
	v_add_f32_e32 v115, 1.0, v115
	v_rcp_f32_e32 v117, v115
	v_pk_mul_f32 v[108:109], v[108:109], v[114:115] op_sel_hi:[1,0]
	v_pk_mul_f32 v[102:103], v[102:103], v[114:115] op_sel_hi:[1,0]
	v_pk_mul_f32 v[98:99], v[98:99], v[114:115] op_sel_hi:[1,0]
	v_pk_mul_f32 v[110:111], v[110:111], v[116:117]
	v_pk_mul_f32 v[100:101], v[100:101], v[114:115] op_sel_hi:[1,0]
	v_pk_mul_f32 v[106:107], v[106:107], v[110:111]
	v_pk_mul_f32 v[110:111], v[112:113], v[114:115] op_sel_hi:[1,0]
	s_nop 0
	v_mul_f32_e32 v112, 0xbfb8aa3b, v110
	v_mul_f32_e32 v113, 0xbfb8aa3b, v111
	v_exp_f32_e32 v112, v112
	v_exp_f32_e32 v113, v113
	v_add_f32_e32 v112, 1.0, v112
	v_add_f32_e32 v113, 1.0, v113
	v_rcp_f32_e32 v112, v112
	v_rcp_f32_e32 v113, v113
	s_nop 0
	v_pk_mul_f32 v[110:111], v[110:111], v[112:113]
	s_nop 0
	v_pk_mul_f32 v[108:109], v[108:109], v[110:111]
	v_mul_f32_e32 v110, 0xbfb8aa3b, v102
	v_mul_f32_e32 v111, 0xbfb8aa3b, v103
	v_exp_f32_e32 v110, v110
	v_exp_f32_e32 v111, v111
	v_add_f32_e32 v110, 1.0, v110
	v_add_f32_e32 v111, 1.0, v111
	v_rcp_f32_e32 v110, v110
	v_rcp_f32_e32 v111, v111
	s_nop 0
	v_pk_mul_f32 v[102:103], v[102:103], v[110:111]
	s_nop 0
	v_pk_mul_f32 v[102:103], v[98:99], v[102:103]
	v_pk_mul_f32 v[98:99], v[104:105], v[114:115] op_sel_hi:[1,0]
	s_nop 0
	v_mul_f32_e32 v104, 0xbfb8aa3b, v98
	v_mul_f32_e32 v105, 0xbfb8aa3b, v99
	v_exp_f32_e32 v104, v104
	v_exp_f32_e32 v105, v105
	v_add_f32_e32 v104, 1.0, v104
	v_add_f32_e32 v105, 1.0, v105
	v_rcp_f32_e32 v104, v104
	v_rcp_f32_e32 v105, v105
	s_nop 0
	v_pk_mul_f32 v[98:99], v[98:99], v[104:105]
	s_nop 0
	v_pk_mul_f32 v[104:105], v[100:101], v[98:99]
	v_cvt_pk_bf16_f32 v100, v102, v103
	v_mad_i64_i32 v[102:103], s[18:19], v159, s71, v[118:119]
	v_cvt_pk_bf16_f32 v98, v106, v107
	v_cvt_pk_bf16_f32 v99, v108, v109
	v_cvt_pk_bf16_f32 v101, v104, v105
	v_lshl_add_u64 v[102:103], v[102:103], 0, v[120:121]
	global_store_dwordx4 v[102:103], v[98:101], off
	s_nop 1
	v_fmamk_f32 v98, v158, 0x3a000000, v214
	v_rsq_f32_e32 v98, v98
	s_nop 0
	v_pk_mul_f32 v[94:95], v[94:95], v[98:99] op_sel_hi:[1,0]
	s_nop 0
	v_mul_f32_e32 v99, 0xbfb8aa3b, v94
	v_exp_f32_e32 v99, v99
	s_nop 0
	v_add_f32_e32 v99, 1.0, v99
	v_rcp_f32_e32 v100, v99
	v_pk_mul_f32 v[90:91], v[90:91], v[98:99] op_sel_hi:[1,0]
	v_mul_f32_e32 v99, 0xbfb8aa3b, v95
	v_exp_f32_e32 v99, v99
	s_nop 0
	v_add_f32_e32 v99, 1.0, v99
	v_rcp_f32_e32 v101, v99
	v_pk_mul_f32 v[92:93], v[92:93], v[98:99] op_sel_hi:[1,0]
	v_pk_mul_f32 v[86:87], v[86:87], v[98:99] op_sel_hi:[1,0]
	v_pk_mul_f32 v[82:83], v[82:83], v[98:99] op_sel_hi:[1,0]
	v_pk_mul_f32 v[94:95], v[94:95], v[100:101]
	v_pk_mul_f32 v[84:85], v[84:85], v[98:99] op_sel_hi:[1,0]
	v_pk_mul_f32 v[90:91], v[90:91], v[94:95]
	v_pk_mul_f32 v[94:95], v[96:97], v[98:99] op_sel_hi:[1,0]
	s_nop 0
	v_mul_f32_e32 v96, 0xbfb8aa3b, v94
	v_mul_f32_e32 v97, 0xbfb8aa3b, v95
	v_exp_f32_e32 v96, v96
	v_exp_f32_e32 v97, v97
	v_add_f32_e32 v96, 1.0, v96
	v_add_f32_e32 v97, 1.0, v97
	v_rcp_f32_e32 v96, v96
	v_rcp_f32_e32 v97, v97
	s_nop 0
	v_pk_mul_f32 v[94:95], v[94:95], v[96:97]
	s_nop 0
	v_pk_mul_f32 v[92:93], v[92:93], v[94:95]
	v_mul_f32_e32 v94, 0xbfb8aa3b, v86
	v_mul_f32_e32 v95, 0xbfb8aa3b, v87
	v_exp_f32_e32 v94, v94
	v_exp_f32_e32 v95, v95
	v_add_f32_e32 v94, 1.0, v94
	v_add_f32_e32 v95, 1.0, v95
	v_rcp_f32_e32 v94, v94
	v_rcp_f32_e32 v95, v95
	s_nop 0
	v_pk_mul_f32 v[86:87], v[86:87], v[94:95]
	s_nop 0
	v_pk_mul_f32 v[86:87], v[82:83], v[86:87]
	v_pk_mul_f32 v[82:83], v[88:89], v[98:99] op_sel_hi:[1,0]
	s_nop 0
	v_mul_f32_e32 v88, 0xbfb8aa3b, v82
	v_mul_f32_e32 v89, 0xbfb8aa3b, v83
	v_exp_f32_e32 v88, v88
	v_exp_f32_e32 v89, v89
	v_add_f32_e32 v88, 1.0, v88
	v_add_f32_e32 v89, 1.0, v89
	v_rcp_f32_e32 v88, v88
	v_rcp_f32_e32 v89, v89
	s_nop 0
	v_pk_mul_f32 v[82:83], v[82:83], v[88:89]
	s_nop 0
	v_pk_mul_f32 v[88:89], v[84:85], v[82:83]
	v_cvt_pk_bf16_f32 v84, v86, v87
	v_mad_i64_i32 v[86:87], s[18:19], v157, s71, v[118:119]
	v_cvt_pk_bf16_f32 v82, v90, v91
	v_cvt_pk_bf16_f32 v83, v92, v93
	v_cvt_pk_bf16_f32 v85, v88, v89
	v_lshl_add_u64 v[86:87], v[86:87], 0, v[120:121]
	global_store_dwordx4 v[86:87], v[82:85], off
	s_nop 1
	v_fmamk_f32 v82, v156, 0x3a000000, v214
	v_rsq_f32_e32 v82, v82
	s_nop 0
	v_pk_mul_f32 v[78:79], v[78:79], v[82:83] op_sel_hi:[1,0]
	s_nop 0
	v_mul_f32_e32 v83, 0xbfb8aa3b, v78
	v_exp_f32_e32 v83, v83
	s_nop 0
	v_add_f32_e32 v83, 1.0, v83
	v_rcp_f32_e32 v84, v83
	v_pk_mul_f32 v[74:75], v[74:75], v[82:83] op_sel_hi:[1,0]
	v_mul_f32_e32 v83, 0xbfb8aa3b, v79
	v_exp_f32_e32 v83, v83
	s_nop 0
	v_add_f32_e32 v83, 1.0, v83
	v_rcp_f32_e32 v85, v83
	v_pk_mul_f32 v[76:77], v[76:77], v[82:83] op_sel_hi:[1,0]
	v_pk_mul_f32 v[70:71], v[70:71], v[82:83] op_sel_hi:[1,0]
	v_pk_mul_f32 v[66:67], v[66:67], v[82:83] op_sel_hi:[1,0]
	v_pk_mul_f32 v[78:79], v[78:79], v[84:85]
	v_pk_mul_f32 v[68:69], v[68:69], v[82:83] op_sel_hi:[1,0]
	v_pk_mul_f32 v[74:75], v[74:75], v[78:79]
	v_pk_mul_f32 v[78:79], v[80:81], v[82:83] op_sel_hi:[1,0]
	s_nop 0
	v_mul_f32_e32 v80, 0xbfb8aa3b, v78
	v_mul_f32_e32 v81, 0xbfb8aa3b, v79
	v_exp_f32_e32 v80, v80
	v_exp_f32_e32 v81, v81
	v_add_f32_e32 v80, 1.0, v80
	v_add_f32_e32 v81, 1.0, v81
	v_rcp_f32_e32 v80, v80
	v_rcp_f32_e32 v81, v81
	s_nop 0
	v_pk_mul_f32 v[78:79], v[78:79], v[80:81]
	s_nop 0
	v_pk_mul_f32 v[76:77], v[76:77], v[78:79]
	v_mul_f32_e32 v78, 0xbfb8aa3b, v70
	v_mul_f32_e32 v79, 0xbfb8aa3b, v71
	v_exp_f32_e32 v78, v78
	v_exp_f32_e32 v79, v79
	v_add_f32_e32 v78, 1.0, v78
	v_add_f32_e32 v79, 1.0, v79
	v_rcp_f32_e32 v78, v78
	v_rcp_f32_e32 v79, v79
	s_nop 0
	v_pk_mul_f32 v[70:71], v[70:71], v[78:79]
	s_nop 0
	v_pk_mul_f32 v[70:71], v[66:67], v[70:71]
	v_pk_mul_f32 v[66:67], v[72:73], v[82:83] op_sel_hi:[1,0]
	s_nop 0
	v_mul_f32_e32 v72, 0xbfb8aa3b, v66
	v_mul_f32_e32 v73, 0xbfb8aa3b, v67
	v_exp_f32_e32 v72, v72
	v_exp_f32_e32 v73, v73
	v_add_f32_e32 v72, 1.0, v72
	v_add_f32_e32 v73, 1.0, v73
	v_rcp_f32_e32 v72, v72
	v_rcp_f32_e32 v73, v73
	s_nop 0
	v_pk_mul_f32 v[66:67], v[66:67], v[72:73]
	s_nop 0
	v_pk_mul_f32 v[72:73], v[68:69], v[66:67]
	v_cvt_pk_bf16_f32 v68, v70, v71
	v_mad_i64_i32 v[70:71], s[18:19], v155, s71, v[118:119]
	v_cvt_pk_bf16_f32 v66, v74, v75
	v_cvt_pk_bf16_f32 v67, v76, v77
	v_cvt_pk_bf16_f32 v69, v72, v73
	v_lshl_add_u64 v[70:71], v[70:71], 0, v[120:121]
	global_store_dwordx4 v[70:71], v[66:69], off
	s_nop 1
	v_fmamk_f32 v66, v154, 0x3a000000, v214
	v_rsq_f32_e32 v66, v66
	s_nop 0
	v_pk_mul_f32 v[62:63], v[62:63], v[66:67] op_sel_hi:[1,0]
	s_nop 0
	v_mul_f32_e32 v67, 0xbfb8aa3b, v62
	v_exp_f32_e32 v67, v67
	s_nop 0
	v_add_f32_e32 v67, 1.0, v67
	v_rcp_f32_e32 v68, v67
	v_pk_mul_f32 v[58:59], v[58:59], v[66:67] op_sel_hi:[1,0]
	v_mul_f32_e32 v67, 0xbfb8aa3b, v63
	v_exp_f32_e32 v67, v67
	s_nop 0
	v_add_f32_e32 v67, 1.0, v67
	v_rcp_f32_e32 v69, v67
	v_pk_mul_f32 v[60:61], v[60:61], v[66:67] op_sel_hi:[1,0]
	v_pk_mul_f32 v[54:55], v[54:55], v[66:67] op_sel_hi:[1,0]
	v_pk_mul_f32 v[50:51], v[50:51], v[66:67] op_sel_hi:[1,0]
	v_pk_mul_f32 v[62:63], v[62:63], v[68:69]
	v_pk_mul_f32 v[52:53], v[52:53], v[66:67] op_sel_hi:[1,0]
	v_pk_mul_f32 v[58:59], v[58:59], v[62:63]
	v_pk_mul_f32 v[62:63], v[64:65], v[66:67] op_sel_hi:[1,0]
	s_nop 0
	v_mul_f32_e32 v64, 0xbfb8aa3b, v62
	v_mul_f32_e32 v65, 0xbfb8aa3b, v63
	v_exp_f32_e32 v64, v64
	v_exp_f32_e32 v65, v65
	v_add_f32_e32 v64, 1.0, v64
	v_add_f32_e32 v65, 1.0, v65
	v_rcp_f32_e32 v64, v64
	v_rcp_f32_e32 v65, v65
	s_nop 0
	v_pk_mul_f32 v[62:63], v[62:63], v[64:65]
	s_nop 0
	v_pk_mul_f32 v[60:61], v[60:61], v[62:63]
	v_mul_f32_e32 v62, 0xbfb8aa3b, v54
	v_mul_f32_e32 v63, 0xbfb8aa3b, v55
	v_exp_f32_e32 v62, v62
	v_exp_f32_e32 v63, v63
	v_add_f32_e32 v62, 1.0, v62
	v_add_f32_e32 v63, 1.0, v63
	v_rcp_f32_e32 v62, v62
	v_rcp_f32_e32 v63, v63
	s_nop 0
	v_pk_mul_f32 v[54:55], v[54:55], v[62:63]
	s_nop 0
	v_pk_mul_f32 v[54:55], v[50:51], v[54:55]
	v_pk_mul_f32 v[50:51], v[56:57], v[66:67] op_sel_hi:[1,0]
	s_nop 0
	v_mul_f32_e32 v56, 0xbfb8aa3b, v50
	v_mul_f32_e32 v57, 0xbfb8aa3b, v51
	v_exp_f32_e32 v56, v56
	v_exp_f32_e32 v57, v57
	v_add_f32_e32 v56, 1.0, v56
	v_add_f32_e32 v57, 1.0, v57
	v_rcp_f32_e32 v56, v56
	v_rcp_f32_e32 v57, v57
	s_nop 0
	v_pk_mul_f32 v[50:51], v[50:51], v[56:57]
	s_nop 0
	v_pk_mul_f32 v[56:57], v[52:53], v[50:51]
	v_cvt_pk_bf16_f32 v52, v54, v55
	v_mad_i64_i32 v[54:55], s[18:19], v153, s71, v[118:119]
	v_cvt_pk_bf16_f32 v50, v58, v59
	v_cvt_pk_bf16_f32 v51, v60, v61
	v_cvt_pk_bf16_f32 v53, v56, v57
	v_lshl_add_u64 v[54:55], v[54:55], 0, v[120:121]
	global_store_dwordx4 v[54:55], v[50:53], off
	s_nop 1
	v_fmamk_f32 v50, v152, 0x3a000000, v214
	v_rsq_f32_e32 v50, v50
	s_nop 0
	v_pk_mul_f32 v[46:47], v[46:47], v[50:51] op_sel_hi:[1,0]
	s_nop 0
	v_mul_f32_e32 v51, 0xbfb8aa3b, v46
	v_exp_f32_e32 v51, v51
	s_nop 0
	v_add_f32_e32 v51, 1.0, v51
	v_rcp_f32_e32 v52, v51
	v_pk_mul_f32 v[42:43], v[42:43], v[50:51] op_sel_hi:[1,0]
	v_mul_f32_e32 v51, 0xbfb8aa3b, v47
	v_exp_f32_e32 v51, v51
	s_nop 0
	v_add_f32_e32 v51, 1.0, v51
	v_rcp_f32_e32 v53, v51
	v_pk_mul_f32 v[44:45], v[44:45], v[50:51] op_sel_hi:[1,0]
	v_pk_mul_f32 v[38:39], v[38:39], v[50:51] op_sel_hi:[1,0]
	v_pk_mul_f32 v[34:35], v[34:35], v[50:51] op_sel_hi:[1,0]
	v_pk_mul_f32 v[46:47], v[46:47], v[52:53]
	v_pk_mul_f32 v[36:37], v[36:37], v[50:51] op_sel_hi:[1,0]
	v_pk_mul_f32 v[42:43], v[42:43], v[46:47]
	v_pk_mul_f32 v[46:47], v[48:49], v[50:51] op_sel_hi:[1,0]
	s_nop 0
	v_mul_f32_e32 v48, 0xbfb8aa3b, v46
	v_mul_f32_e32 v49, 0xbfb8aa3b, v47
	v_exp_f32_e32 v48, v48
	v_exp_f32_e32 v49, v49
	v_add_f32_e32 v48, 1.0, v48
	v_add_f32_e32 v49, 1.0, v49
	v_rcp_f32_e32 v48, v48
	v_rcp_f32_e32 v49, v49
	s_nop 0
	v_pk_mul_f32 v[46:47], v[46:47], v[48:49]
	s_nop 0
	v_pk_mul_f32 v[44:45], v[44:45], v[46:47]
	v_mul_f32_e32 v46, 0xbfb8aa3b, v38
	v_mul_f32_e32 v47, 0xbfb8aa3b, v39
	v_exp_f32_e32 v46, v46
	v_exp_f32_e32 v47, v47
	v_add_f32_e32 v46, 1.0, v46
	v_add_f32_e32 v47, 1.0, v47
	v_rcp_f32_e32 v46, v46
	v_rcp_f32_e32 v47, v47
	s_nop 0
	v_pk_mul_f32 v[38:39], v[38:39], v[46:47]
	s_nop 0
	v_pk_mul_f32 v[38:39], v[34:35], v[38:39]
	v_pk_mul_f32 v[34:35], v[40:41], v[50:51] op_sel_hi:[1,0]
	s_nop 0
	v_mul_f32_e32 v40, 0xbfb8aa3b, v34
	v_mul_f32_e32 v41, 0xbfb8aa3b, v35
	v_exp_f32_e32 v40, v40
	v_exp_f32_e32 v41, v41
	v_add_f32_e32 v40, 1.0, v40
	v_add_f32_e32 v41, 1.0, v41
	v_rcp_f32_e32 v40, v40
	v_rcp_f32_e32 v41, v41
	s_nop 0
	v_pk_mul_f32 v[34:35], v[34:35], v[40:41]
	s_nop 0
	v_pk_mul_f32 v[40:41], v[36:37], v[34:35]
	v_cvt_pk_bf16_f32 v36, v38, v39
	v_mad_i64_i32 v[38:39], s[18:19], v151, s71, v[118:119]
	v_cvt_pk_bf16_f32 v34, v42, v43
	v_cvt_pk_bf16_f32 v35, v44, v45
	v_cvt_pk_bf16_f32 v37, v40, v41
	v_lshl_add_u64 v[38:39], v[38:39], 0, v[120:121]
	global_store_dwordx4 v[38:39], v[34:37], off
	s_nop 1
	v_fmamk_f32 v34, v150, 0x3a000000, v214
	v_rsq_f32_e32 v34, v34
	s_nop 0
	v_pk_mul_f32 v[30:31], v[30:31], v[34:35] op_sel_hi:[1,0]
	s_nop 0
	v_mul_f32_e32 v35, 0xbfb8aa3b, v30
	v_exp_f32_e32 v35, v35
	s_nop 0
	v_add_f32_e32 v35, 1.0, v35
	v_rcp_f32_e32 v36, v35
	v_pk_mul_f32 v[26:27], v[26:27], v[34:35] op_sel_hi:[1,0]
	v_mul_f32_e32 v35, 0xbfb8aa3b, v31
	v_exp_f32_e32 v35, v35
	s_nop 0
	v_add_f32_e32 v35, 1.0, v35
	v_rcp_f32_e32 v37, v35
	v_pk_mul_f32 v[28:29], v[28:29], v[34:35] op_sel_hi:[1,0]
	v_pk_mul_f32 v[22:23], v[22:23], v[34:35] op_sel_hi:[1,0]
	v_pk_mul_f32 v[18:19], v[18:19], v[34:35] op_sel_hi:[1,0]
	v_pk_mul_f32 v[30:31], v[30:31], v[36:37]
	v_pk_mul_f32 v[20:21], v[20:21], v[34:35] op_sel_hi:[1,0]
	v_pk_mul_f32 v[26:27], v[26:27], v[30:31]
	v_pk_mul_f32 v[30:31], v[32:33], v[34:35] op_sel_hi:[1,0]
	s_nop 0
	v_mul_f32_e32 v32, 0xbfb8aa3b, v30
	v_mul_f32_e32 v33, 0xbfb8aa3b, v31
	v_exp_f32_e32 v32, v32
	v_exp_f32_e32 v33, v33
	v_add_f32_e32 v32, 1.0, v32
	v_add_f32_e32 v33, 1.0, v33
	v_rcp_f32_e32 v32, v32
	v_rcp_f32_e32 v33, v33
	s_nop 0
	v_pk_mul_f32 v[30:31], v[30:31], v[32:33]
	s_nop 0
	v_pk_mul_f32 v[28:29], v[28:29], v[30:31]
	v_mul_f32_e32 v30, 0xbfb8aa3b, v22
	v_mul_f32_e32 v31, 0xbfb8aa3b, v23
	v_exp_f32_e32 v30, v30
	v_exp_f32_e32 v31, v31
	v_add_f32_e32 v30, 1.0, v30
	v_add_f32_e32 v31, 1.0, v31
	v_rcp_f32_e32 v30, v30
	v_rcp_f32_e32 v31, v31
	s_nop 0
	v_pk_mul_f32 v[22:23], v[22:23], v[30:31]
	s_nop 0
	v_pk_mul_f32 v[22:23], v[18:19], v[22:23]
	v_pk_mul_f32 v[18:19], v[24:25], v[34:35] op_sel_hi:[1,0]
	s_nop 0
	v_mul_f32_e32 v24, 0xbfb8aa3b, v18
	v_mul_f32_e32 v25, 0xbfb8aa3b, v19
	v_exp_f32_e32 v24, v24
	v_exp_f32_e32 v25, v25
	v_add_f32_e32 v24, 1.0, v24
	v_add_f32_e32 v25, 1.0, v25
	v_rcp_f32_e32 v24, v24
	v_rcp_f32_e32 v25, v25
	s_nop 0
	v_pk_mul_f32 v[18:19], v[18:19], v[24:25]
	s_nop 0
	v_pk_mul_f32 v[24:25], v[20:21], v[18:19]
	v_cvt_pk_bf16_f32 v20, v22, v23
	v_mad_i64_i32 v[22:23], s[18:19], v149, s71, v[118:119]
	v_cvt_pk_bf16_f32 v18, v26, v27
	v_cvt_pk_bf16_f32 v19, v28, v29
	v_cvt_pk_bf16_f32 v21, v24, v25
	v_lshl_add_u64 v[22:23], v[22:23], 0, v[120:121]
	global_store_dwordx4 v[22:23], v[18:21], off
	s_nop 1
	v_fmamk_f32 v18, v148, 0x3a000000, v214
	v_rsq_f32_e32 v18, v18
	s_nop 0
	v_pk_mul_f32 v[14:15], v[14:15], v[18:19] op_sel_hi:[1,0]
	s_nop 0
	v_mul_f32_e32 v19, 0xbfb8aa3b, v14
	v_exp_f32_e32 v19, v19
	s_nop 0
	v_add_f32_e32 v19, 1.0, v19
	v_rcp_f32_e32 v20, v19
	v_pk_mul_f32 v[10:11], v[10:11], v[18:19] op_sel_hi:[1,0]
	v_mul_f32_e32 v19, 0xbfb8aa3b, v15
	v_exp_f32_e32 v19, v19
	s_nop 0
	v_add_f32_e32 v19, 1.0, v19
	v_rcp_f32_e32 v21, v19
	v_pk_mul_f32 v[12:13], v[12:13], v[18:19] op_sel_hi:[1,0]
	v_pk_mul_f32 v[6:7], v[6:7], v[18:19] op_sel_hi:[1,0]
	v_pk_mul_f32 v[2:3], v[2:3], v[18:19] op_sel_hi:[1,0]
	v_pk_mul_f32 v[14:15], v[14:15], v[20:21]
	v_pk_mul_f32 v[4:5], v[4:5], v[18:19] op_sel_hi:[1,0]
	v_pk_mul_f32 v[10:11], v[10:11], v[14:15]
	v_pk_mul_f32 v[14:15], v[16:17], v[18:19] op_sel_hi:[1,0]
	s_nop 0
	v_mul_f32_e32 v16, 0xbfb8aa3b, v14
	v_mul_f32_e32 v17, 0xbfb8aa3b, v15
	v_exp_f32_e32 v16, v16
	v_exp_f32_e32 v17, v17
	v_add_f32_e32 v16, 1.0, v16
	v_add_f32_e32 v17, 1.0, v17
	v_rcp_f32_e32 v16, v16
	v_rcp_f32_e32 v17, v17
	s_nop 0
	v_pk_mul_f32 v[14:15], v[14:15], v[16:17]
	s_nop 0
	v_pk_mul_f32 v[12:13], v[12:13], v[14:15]
	v_mul_f32_e32 v14, 0xbfb8aa3b, v6
	v_mul_f32_e32 v15, 0xbfb8aa3b, v7
	v_exp_f32_e32 v14, v14
	v_exp_f32_e32 v15, v15
	v_add_f32_e32 v14, 1.0, v14
	v_add_f32_e32 v15, 1.0, v15
	v_rcp_f32_e32 v14, v14
	v_rcp_f32_e32 v15, v15
	s_nop 0
	v_pk_mul_f32 v[6:7], v[6:7], v[14:15]
	s_nop 0
	v_pk_mul_f32 v[6:7], v[2:3], v[6:7]
	v_pk_mul_f32 v[2:3], v[8:9], v[18:19] op_sel_hi:[1,0]
	s_nop 0
	v_mul_f32_e32 v8, 0xbfb8aa3b, v2
	v_mul_f32_e32 v9, 0xbfb8aa3b, v3
	v_exp_f32_e32 v8, v8
	v_exp_f32_e32 v9, v9
	v_add_f32_e32 v8, 1.0, v8
	v_add_f32_e32 v9, 1.0, v9
	v_rcp_f32_e32 v8, v8
	v_rcp_f32_e32 v9, v9
	s_nop 0
	v_pk_mul_f32 v[2:3], v[2:3], v[8:9]
	s_nop 0
	v_pk_mul_f32 v[8:9], v[4:5], v[2:3]
	v_cvt_pk_bf16_f32 v4, v6, v7
	v_mad_i64_i32 v[6:7], s[18:19], v141, s71, v[118:119]
	v_cvt_pk_bf16_f32 v2, v10, v11
	v_cvt_pk_bf16_f32 v3, v12, v13
	v_cvt_pk_bf16_f32 v5, v8, v9
	v_lshl_add_u64 v[6:7], v[6:7], 0, v[120:121]
	s_mov_b64 s[18:19], -1
	global_store_dwordx4 v[6:7], v[2:5], off
	s_cbranch_vccnz .LBB0_1467
	s_andn2_b64 vcc, exec, s[0:1]
	s_cbranch_vccnz .LBB0_1466
	s_barrier
	s_branch .LBB0_1466
